# BR epilogue rewritten: all 16 gate-value loads hoisted ahead of the in-place stores
# speedup vs baseline: 1.0249x; 1.0014x over previous
.LBB0_913:
	s_lshl_b32 s13, s40, 8
	v_add_u32_e32 v148, s13, v142
	v_mov_b64_e32 v[140:141], s[6:7]
	v_mad_i64_i32 v[150:151], s[20:21], v148, s68, v[140:141]
	s_lshl_b32 s20, s39, 10
	s_ashr_i32 s21, s20, 31
	s_lshl_b32 s22, s38, 8
	s_lshl_b64 s[20:21], s[20:21], 1
	s_ashr_i32 s23, s22, 31
	v_lshl_add_u64 v[150:151], v[150:151], 0, s[20:21]
	s_lshl_b64 s[22:23], s[22:23], 1
	v_lshl_add_u64 v[150:151], v[150:151], 0, s[22:23]
	v_lshl_add_u64 v[150:151], v[150:151], 0, s[96:97]
	v_lshl_add_u64 v[150:151], v[150:151], 0, v[184:185]
	s_mov_b32 s52, 0x48000
	s_mov_b32 s53, 0
	s_mov_b32 s62, 0x168000
	s_mov_b32 s63, 0
	v_lshl_add_u64 v[152:153], v[150:151], 0, s[52:53]
	v_lshl_add_u64 v[154:155], v[152:153], 0, s[52:53]
	v_lshl_add_u64 v[156:157], v[154:155], 0, s[52:53]
	v_lshl_add_u64 v[158:159], v[156:157], 0, s[62:63]
	v_lshl_add_u64 v[182:183], v[158:159], 0, s[52:53]
	v_lshl_add_u64 v[240:241], v[182:183], 0, s[52:53]
	v_lshl_add_u64 v[140:141], v[240:241], 0, s[52:53]
	v_add_co_u32_e32 v148, vcc, s50, v150
	s_nop 1
	v_addc_co_u32_e32 v149, vcc, 0, v151, vcc
	global_load_dwordx4 v[162:165], v[148:149], off
	v_lshl_add_u64 v[148:149], v[150:151], 0, s[58:59]
	global_load_dwordx4 v[166:169], v[148:149], off offset:256
	v_add_co_u32_e32 v148, vcc, s50, v152
	s_nop 1
	v_addc_co_u32_e32 v149, vcc, 0, v153, vcc
	global_load_dwordx4 v[170:173], v[148:149], off
	v_lshl_add_u64 v[148:149], v[152:153], 0, s[58:59]
	global_load_dwordx4 v[174:177], v[148:149], off offset:256
	v_add_co_u32_e32 v148, vcc, s50, v154
	s_nop 1
	v_addc_co_u32_e32 v149, vcc, 0, v155, vcc
	global_load_dwordx4 v[178:181], v[148:149], off
	v_lshl_add_u64 v[148:149], v[154:155], 0, s[58:59]
	global_load_dwordx4 v[186:189], v[148:149], off offset:256
	v_add_co_u32_e32 v148, vcc, s50, v156
	s_nop 1
	v_addc_co_u32_e32 v149, vcc, 0, v157, vcc
	global_load_dwordx4 v[190:193], v[148:149], off
	v_lshl_add_u64 v[148:149], v[156:157], 0, s[58:59]
	global_load_dwordx4 v[196:199], v[148:149], off offset:256
	v_add_co_u32_e32 v148, vcc, s50, v158
	s_nop 1
	v_addc_co_u32_e32 v149, vcc, 0, v159, vcc
	global_load_dwordx4 v[200:203], v[148:149], off
	v_lshl_add_u64 v[148:149], v[158:159], 0, s[58:59]
	global_load_dwordx4 v[204:207], v[148:149], off offset:256
	v_add_co_u32_e32 v148, vcc, s50, v182
	s_nop 1
	v_addc_co_u32_e32 v149, vcc, 0, v183, vcc
	global_load_dwordx4 v[208:211], v[148:149], off
	v_lshl_add_u64 v[148:149], v[182:183], 0, s[58:59]
	global_load_dwordx4 v[224:227], v[148:149], off offset:256
	v_add_co_u32_e32 v148, vcc, s50, v240
	s_nop 1
	v_addc_co_u32_e32 v149, vcc, 0, v241, vcc
	global_load_dwordx4 v[228:231], v[148:149], off
	v_lshl_add_u64 v[148:149], v[240:241], 0, s[58:59]
	global_load_dwordx4 v[232:235], v[148:149], off offset:256
	v_add_co_u32_e32 v148, vcc, s50, v140
	s_nop 1
	v_addc_co_u32_e32 v149, vcc, 0, v141, vcc
	global_load_dwordx4 v[236:239], v[148:149], off
	s_waitcnt vmcnt(13)
	v_lshlrev_b32_e32 v160, 16, v162
	v_and_b32_e32 v162, 0xffff0000, v162
	v_lshlrev_b32_e32 v161, 16, v163
	v_and_b32_e32 v163, 0xffff0000, v163
	v_lshlrev_b32_e32 v194, 16, v164
	v_and_b32_e32 v164, 0xffff0000, v164
	v_lshlrev_b32_e32 v212, 16, v165
	v_and_b32_e32 v165, 0xffff0000, v165
	v_mul_f32_e32 v124, v124, v160
	v_mul_f32_e32 v125, v125, v162
	v_mul_f32_e32 v126, v126, v161
	v_mul_f32_e32 v127, v127, v163
	v_mul_f32_e32 v120, v120, v194
	v_mul_f32_e32 v121, v121, v164
	v_mul_f32_e32 v122, v122, v212
	v_mul_f32_e32 v123, v123, v165
	v_cvt_pk_bf16_f32 v162, v124, v125
	v_cvt_pk_bf16_f32 v163, v126, v127
	v_cvt_pk_bf16_f32 v164, v120, v121
	v_cvt_pk_bf16_f32 v165, v122, v123
	v_add_co_u32_e32 v148, vcc, s50, v150
	s_nop 1
	v_addc_co_u32_e32 v149, vcc, 0, v151, vcc
	global_store_dwordx4 v[148:149], v[162:165], off
	v_lshlrev_b32_e32 v160, 16, v166
	v_and_b32_e32 v166, 0xffff0000, v166
	v_lshlrev_b32_e32 v161, 16, v167
	v_and_b32_e32 v167, 0xffff0000, v167
	v_lshlrev_b32_e32 v194, 16, v168
	v_and_b32_e32 v168, 0xffff0000, v168
	v_lshlrev_b32_e32 v212, 16, v169
	v_and_b32_e32 v169, 0xffff0000, v169
	v_mul_f32_e32 v116, v116, v160
	v_mul_f32_e32 v117, v117, v166
	v_mul_f32_e32 v118, v118, v161
	v_mul_f32_e32 v119, v119, v167
	v_mul_f32_e32 v112, v112, v194
	v_mul_f32_e32 v113, v113, v168
	v_mul_f32_e32 v114, v114, v212
	v_mul_f32_e32 v115, v115, v169
	v_cvt_pk_bf16_f32 v166, v116, v117
	v_cvt_pk_bf16_f32 v167, v118, v119
	v_cvt_pk_bf16_f32 v168, v112, v113
	v_cvt_pk_bf16_f32 v169, v114, v115
	v_lshl_add_u64 v[148:149], v[150:151], 0, s[58:59]
	global_store_dwordx4 v[148:149], v[166:169], off offset:256
	v_lshl_add_u64 v[148:149], v[140:141], 0, s[58:59]
	global_load_dwordx4 v[162:165], v[148:149], off offset:256
	s_waitcnt vmcnt(14)
	v_lshlrev_b32_e32 v160, 16, v170
	v_and_b32_e32 v170, 0xffff0000, v170
	v_lshlrev_b32_e32 v161, 16, v171
	v_and_b32_e32 v171, 0xffff0000, v171
	v_lshlrev_b32_e32 v194, 16, v172
	v_and_b32_e32 v172, 0xffff0000, v172
	v_lshlrev_b32_e32 v212, 16, v173
	v_and_b32_e32 v173, 0xffff0000, v173
	v_mul_f32_e32 v108, v108, v160
	v_mul_f32_e32 v109, v109, v170
	v_mul_f32_e32 v110, v110, v161
	v_mul_f32_e32 v111, v111, v171
	v_mul_f32_e32 v104, v104, v194
	v_mul_f32_e32 v105, v105, v172
	v_mul_f32_e32 v106, v106, v212
	v_mul_f32_e32 v107, v107, v173
	v_cvt_pk_bf16_f32 v170, v108, v109
	v_cvt_pk_bf16_f32 v171, v110, v111
	v_cvt_pk_bf16_f32 v172, v104, v105
	v_cvt_pk_bf16_f32 v173, v106, v107
	v_add_co_u32_e32 v148, vcc, s50, v152
	s_nop 1
	v_addc_co_u32_e32 v149, vcc, 0, v153, vcc
	global_store_dwordx4 v[148:149], v[170:173], off
	v_lshlrev_b32_e32 v160, 16, v174
	v_and_b32_e32 v174, 0xffff0000, v174
	v_lshlrev_b32_e32 v161, 16, v175
	v_and_b32_e32 v175, 0xffff0000, v175
	v_lshlrev_b32_e32 v194, 16, v176
	v_and_b32_e32 v176, 0xffff0000, v176
	v_lshlrev_b32_e32 v212, 16, v177
	v_and_b32_e32 v177, 0xffff0000, v177
	v_mul_f32_e32 v100, v100, v160
	v_mul_f32_e32 v101, v101, v174
	v_mul_f32_e32 v102, v102, v161
	v_mul_f32_e32 v103, v103, v175
	v_mul_f32_e32 v96, v96, v194
	v_mul_f32_e32 v97, v97, v176
	v_mul_f32_e32 v98, v98, v212
	v_mul_f32_e32 v99, v99, v177
	v_cvt_pk_bf16_f32 v174, v100, v101
	v_cvt_pk_bf16_f32 v175, v102, v103
	v_cvt_pk_bf16_f32 v176, v96, v97
	v_cvt_pk_bf16_f32 v177, v98, v99
	v_lshl_add_u64 v[148:149], v[152:153], 0, s[58:59]
	global_store_dwordx4 v[148:149], v[174:177], off offset:256
	s_waitcnt vmcnt(14)
	v_lshlrev_b32_e32 v160, 16, v178
	v_and_b32_e32 v178, 0xffff0000, v178
	v_lshlrev_b32_e32 v161, 16, v179
	v_and_b32_e32 v179, 0xffff0000, v179
	v_lshlrev_b32_e32 v194, 16, v180
	v_and_b32_e32 v180, 0xffff0000, v180
	v_lshlrev_b32_e32 v212, 16, v181
	v_and_b32_e32 v181, 0xffff0000, v181
	v_mul_f32_e32 v92, v92, v160
	v_mul_f32_e32 v93, v93, v178
	v_mul_f32_e32 v94, v94, v161
	v_mul_f32_e32 v95, v95, v179
	v_mul_f32_e32 v88, v88, v194
	v_mul_f32_e32 v89, v89, v180
	v_mul_f32_e32 v90, v90, v212
	v_mul_f32_e32 v91, v91, v181
	v_cvt_pk_bf16_f32 v178, v92, v93
	v_cvt_pk_bf16_f32 v179, v94, v95
	v_cvt_pk_bf16_f32 v180, v88, v89
	v_cvt_pk_bf16_f32 v181, v90, v91
	v_add_co_u32_e32 v148, vcc, s50, v154
	s_nop 1
	v_addc_co_u32_e32 v149, vcc, 0, v155, vcc
	global_store_dwordx4 v[148:149], v[178:181], off
	v_lshlrev_b32_e32 v160, 16, v186
	v_and_b32_e32 v186, 0xffff0000, v186
	v_lshlrev_b32_e32 v161, 16, v187
	v_and_b32_e32 v187, 0xffff0000, v187
	v_lshlrev_b32_e32 v194, 16, v188
	v_and_b32_e32 v188, 0xffff0000, v188
	v_lshlrev_b32_e32 v212, 16, v189
	v_and_b32_e32 v189, 0xffff0000, v189
	v_mul_f32_e32 v84, v84, v160
	v_mul_f32_e32 v85, v85, v186
	v_mul_f32_e32 v86, v86, v161
	v_mul_f32_e32 v87, v87, v187
	v_mul_f32_e32 v80, v80, v194
	v_mul_f32_e32 v81, v81, v188
	v_mul_f32_e32 v82, v82, v212
	v_mul_f32_e32 v83, v83, v189
	v_cvt_pk_bf16_f32 v186, v84, v85
	v_cvt_pk_bf16_f32 v187, v86, v87
	v_cvt_pk_bf16_f32 v188, v80, v81
	v_cvt_pk_bf16_f32 v189, v82, v83
	v_lshl_add_u64 v[148:149], v[154:155], 0, s[58:59]
	global_store_dwordx4 v[148:149], v[186:189], off offset:256
	s_waitcnt vmcnt(14)
	v_lshlrev_b32_e32 v160, 16, v190
	v_and_b32_e32 v190, 0xffff0000, v190
	v_lshlrev_b32_e32 v161, 16, v191
	v_and_b32_e32 v191, 0xffff0000, v191
	v_lshlrev_b32_e32 v194, 16, v192
	v_and_b32_e32 v192, 0xffff0000, v192
	v_lshlrev_b32_e32 v212, 16, v193
	v_and_b32_e32 v193, 0xffff0000, v193
	v_mul_f32_e32 v76, v76, v160
	v_mul_f32_e32 v77, v77, v190
	v_mul_f32_e32 v78, v78, v161
	v_mul_f32_e32 v79, v79, v191
	v_mul_f32_e32 v72, v72, v194
	v_mul_f32_e32 v73, v73, v192
	v_mul_f32_e32 v74, v74, v212
	v_mul_f32_e32 v75, v75, v193
	v_cvt_pk_bf16_f32 v190, v76, v77
	v_cvt_pk_bf16_f32 v191, v78, v79
	v_cvt_pk_bf16_f32 v192, v72, v73
	v_cvt_pk_bf16_f32 v193, v74, v75
	v_add_co_u32_e32 v148, vcc, s50, v156
	s_nop 1
	v_addc_co_u32_e32 v149, vcc, 0, v157, vcc
	global_store_dwordx4 v[148:149], v[190:193], off
	v_lshlrev_b32_e32 v160, 16, v196
	v_and_b32_e32 v196, 0xffff0000, v196
	v_lshlrev_b32_e32 v161, 16, v197
	v_and_b32_e32 v197, 0xffff0000, v197
	v_lshlrev_b32_e32 v194, 16, v198
	v_and_b32_e32 v198, 0xffff0000, v198
	v_lshlrev_b32_e32 v212, 16, v199
	v_and_b32_e32 v199, 0xffff0000, v199
	v_mul_f32_e32 v68, v68, v160
	v_mul_f32_e32 v69, v69, v196
	v_mul_f32_e32 v70, v70, v161
	v_mul_f32_e32 v71, v71, v197
	v_mul_f32_e32 v64, v64, v194
	v_mul_f32_e32 v65, v65, v198
	v_mul_f32_e32 v66, v66, v212
	v_mul_f32_e32 v67, v67, v199
	v_cvt_pk_bf16_f32 v196, v68, v69
	v_cvt_pk_bf16_f32 v197, v70, v71
	v_cvt_pk_bf16_f32 v198, v64, v65
	v_cvt_pk_bf16_f32 v199, v66, v67
	v_lshl_add_u64 v[148:149], v[156:157], 0, s[58:59]
	global_store_dwordx4 v[148:149], v[196:199], off offset:256
	s_waitcnt vmcnt(14)
	v_lshlrev_b32_e32 v160, 16, v200
	v_and_b32_e32 v200, 0xffff0000, v200
	v_lshlrev_b32_e32 v161, 16, v201
	v_and_b32_e32 v201, 0xffff0000, v201
	v_lshlrev_b32_e32 v194, 16, v202
	v_and_b32_e32 v202, 0xffff0000, v202
	v_lshlrev_b32_e32 v212, 16, v203
	v_and_b32_e32 v203, 0xffff0000, v203
	v_mul_f32_e32 v60, v60, v160
	v_mul_f32_e32 v61, v61, v200
	v_mul_f32_e32 v62, v62, v161
	v_mul_f32_e32 v63, v63, v201
	v_mul_f32_e32 v56, v56, v194
	v_mul_f32_e32 v57, v57, v202
	v_mul_f32_e32 v58, v58, v212
	v_mul_f32_e32 v59, v59, v203
	v_cvt_pk_bf16_f32 v200, v60, v61
	v_cvt_pk_bf16_f32 v201, v62, v63
	v_cvt_pk_bf16_f32 v202, v56, v57
	v_cvt_pk_bf16_f32 v203, v58, v59
	v_add_co_u32_e32 v148, vcc, s50, v158
	s_nop 1
	v_addc_co_u32_e32 v149, vcc, 0, v159, vcc
	global_store_dwordx4 v[148:149], v[200:203], off
	v_lshlrev_b32_e32 v160, 16, v204
	v_and_b32_e32 v204, 0xffff0000, v204
	v_lshlrev_b32_e32 v161, 16, v205
	v_and_b32_e32 v205, 0xffff0000, v205
	v_lshlrev_b32_e32 v194, 16, v206
	v_and_b32_e32 v206, 0xffff0000, v206
	v_lshlrev_b32_e32 v212, 16, v207
	v_and_b32_e32 v207, 0xffff0000, v207
	v_mul_f32_e32 v52, v52, v160
	v_mul_f32_e32 v53, v53, v204
	v_mul_f32_e32 v54, v54, v161
	v_mul_f32_e32 v55, v55, v205
	v_mul_f32_e32 v48, v48, v194
	v_mul_f32_e32 v49, v49, v206
	v_mul_f32_e32 v50, v50, v212
	v_mul_f32_e32 v51, v51, v207
	v_cvt_pk_bf16_f32 v204, v52, v53
	v_cvt_pk_bf16_f32 v205, v54, v55
	v_cvt_pk_bf16_f32 v206, v48, v49
	v_cvt_pk_bf16_f32 v207, v50, v51
	v_lshl_add_u64 v[148:149], v[158:159], 0, s[58:59]
	global_store_dwordx4 v[148:149], v[204:207], off offset:256
	s_waitcnt vmcnt(14)
	v_lshlrev_b32_e32 v160, 16, v208
	v_and_b32_e32 v208, 0xffff0000, v208
	v_lshlrev_b32_e32 v161, 16, v209
	v_and_b32_e32 v209, 0xffff0000, v209
	v_lshlrev_b32_e32 v194, 16, v210
	v_and_b32_e32 v210, 0xffff0000, v210
	v_lshlrev_b32_e32 v212, 16, v211
	v_and_b32_e32 v211, 0xffff0000, v211
	v_mul_f32_e32 v44, v44, v160
	v_mul_f32_e32 v45, v45, v208
	v_mul_f32_e32 v46, v46, v161
	v_mul_f32_e32 v47, v47, v209
	v_mul_f32_e32 v40, v40, v194
	v_mul_f32_e32 v41, v41, v210
	v_mul_f32_e32 v42, v42, v212
	v_mul_f32_e32 v43, v43, v211
	v_cvt_pk_bf16_f32 v208, v44, v45
	v_cvt_pk_bf16_f32 v209, v46, v47
	v_cvt_pk_bf16_f32 v210, v40, v41
	v_cvt_pk_bf16_f32 v211, v42, v43
	v_add_co_u32_e32 v148, vcc, s50, v182
	s_nop 1
	v_addc_co_u32_e32 v149, vcc, 0, v183, vcc
	global_store_dwordx4 v[148:149], v[208:211], off
	v_lshlrev_b32_e32 v160, 16, v224
	v_and_b32_e32 v224, 0xffff0000, v224
	v_lshlrev_b32_e32 v161, 16, v225
	v_and_b32_e32 v225, 0xffff0000, v225
	v_lshlrev_b32_e32 v194, 16, v226
	v_and_b32_e32 v226, 0xffff0000, v226
	v_lshlrev_b32_e32 v212, 16, v227
	v_and_b32_e32 v227, 0xffff0000, v227
	v_mul_f32_e32 v36, v36, v160
	v_mul_f32_e32 v37, v37, v224
	v_mul_f32_e32 v38, v38, v161
	v_mul_f32_e32 v39, v39, v225
	v_mul_f32_e32 v32, v32, v194
	v_mul_f32_e32 v33, v33, v226
	v_mul_f32_e32 v34, v34, v212
	v_mul_f32_e32 v35, v35, v227
	v_cvt_pk_bf16_f32 v224, v36, v37
	v_cvt_pk_bf16_f32 v225, v38, v39
	v_cvt_pk_bf16_f32 v226, v32, v33
	v_cvt_pk_bf16_f32 v227, v34, v35
	v_lshl_add_u64 v[148:149], v[182:183], 0, s[58:59]
	global_store_dwordx4 v[148:149], v[224:227], off offset:256
	s_waitcnt vmcnt(14)
	v_lshlrev_b32_e32 v160, 16, v228
	v_and_b32_e32 v228, 0xffff0000, v228
	v_lshlrev_b32_e32 v161, 16, v229
	v_and_b32_e32 v229, 0xffff0000, v229
	v_lshlrev_b32_e32 v194, 16, v230
	v_and_b32_e32 v230, 0xffff0000, v230
	v_lshlrev_b32_e32 v212, 16, v231
	v_and_b32_e32 v231, 0xffff0000, v231
	v_mul_f32_e32 v28, v28, v160
	v_mul_f32_e32 v29, v29, v228
	v_mul_f32_e32 v30, v30, v161
	v_mul_f32_e32 v31, v31, v229
	v_mul_f32_e32 v24, v24, v194
	v_mul_f32_e32 v25, v25, v230
	v_mul_f32_e32 v26, v26, v212
	v_mul_f32_e32 v27, v27, v231
	v_cvt_pk_bf16_f32 v228, v28, v29
	v_cvt_pk_bf16_f32 v229, v30, v31
	v_cvt_pk_bf16_f32 v230, v24, v25
	v_cvt_pk_bf16_f32 v231, v26, v27
	v_add_co_u32_e32 v148, vcc, s50, v240
	s_nop 1
	v_addc_co_u32_e32 v149, vcc, 0, v241, vcc
	global_store_dwordx4 v[148:149], v[228:231], off
	v_lshlrev_b32_e32 v160, 16, v232
	v_and_b32_e32 v232, 0xffff0000, v232
	v_lshlrev_b32_e32 v161, 16, v233
	v_and_b32_e32 v233, 0xffff0000, v233
	v_lshlrev_b32_e32 v194, 16, v234
	v_and_b32_e32 v234, 0xffff0000, v234
	v_lshlrev_b32_e32 v212, 16, v235
	v_and_b32_e32 v235, 0xffff0000, v235
	v_mul_f32_e32 v20, v20, v160
	v_mul_f32_e32 v21, v21, v232
	v_mul_f32_e32 v22, v22, v161
	v_mul_f32_e32 v23, v23, v233
	v_mul_f32_e32 v16, v16, v194
	v_mul_f32_e32 v17, v17, v234
	v_mul_f32_e32 v18, v18, v212
	v_mul_f32_e32 v19, v19, v235
	v_cvt_pk_bf16_f32 v232, v20, v21
	v_cvt_pk_bf16_f32 v233, v22, v23
	v_cvt_pk_bf16_f32 v234, v16, v17
	v_cvt_pk_bf16_f32 v235, v18, v19
	v_lshl_add_u64 v[148:149], v[240:241], 0, s[58:59]
	global_store_dwordx4 v[148:149], v[232:235], off offset:256
	s_waitcnt vmcnt(12)
	v_lshlrev_b32_e32 v160, 16, v236
	v_and_b32_e32 v236, 0xffff0000, v236
	v_lshlrev_b32_e32 v161, 16, v237
	v_and_b32_e32 v237, 0xffff0000, v237
	v_lshlrev_b32_e32 v194, 16, v238
	v_and_b32_e32 v238, 0xffff0000, v238
	v_lshlrev_b32_e32 v212, 16, v239
	v_and_b32_e32 v239, 0xffff0000, v239
	v_mul_f32_e32 v12, v12, v160
	v_mul_f32_e32 v13, v13, v236
	v_mul_f32_e32 v14, v14, v161
	v_mul_f32_e32 v15, v15, v237
	v_mul_f32_e32 v8, v8, v194
	v_mul_f32_e32 v9, v9, v238
	v_mul_f32_e32 v10, v10, v212
	v_mul_f32_e32 v11, v11, v239
	v_cvt_pk_bf16_f32 v236, v12, v13
	v_cvt_pk_bf16_f32 v237, v14, v15
	v_cvt_pk_bf16_f32 v238, v8, v9
	v_cvt_pk_bf16_f32 v239, v10, v11
	v_add_co_u32_e32 v148, vcc, s50, v140
	s_nop 1
	v_addc_co_u32_e32 v149, vcc, 0, v141, vcc
	global_store_dwordx4 v[148:149], v[236:239], off
	v_lshlrev_b32_e32 v160, 16, v162
	v_and_b32_e32 v162, 0xffff0000, v162
	v_lshlrev_b32_e32 v161, 16, v163
	v_and_b32_e32 v163, 0xffff0000, v163
	v_lshlrev_b32_e32 v194, 16, v164
	v_and_b32_e32 v164, 0xffff0000, v164
	v_lshlrev_b32_e32 v212, 16, v165
	v_and_b32_e32 v165, 0xffff0000, v165
	v_mul_f32_e32 v4, v4, v160
	v_mul_f32_e32 v5, v5, v162
	v_mul_f32_e32 v6, v6, v161
	v_mul_f32_e32 v7, v7, v163
	v_mul_f32_e32 v0, v0, v194
	v_mul_f32_e32 v1, v1, v164
	v_mul_f32_e32 v2, v2, v212
	v_mul_f32_e32 v3, v3, v165
	v_cvt_pk_bf16_f32 v162, v4, v5
	v_cvt_pk_bf16_f32 v163, v6, v7
	v_cvt_pk_bf16_f32 v164, v0, v1
	v_cvt_pk_bf16_f32 v165, v2, v3
	v_lshl_add_u64 v[148:149], v[140:141], 0, s[58:59]
	global_store_dwordx4 v[148:149], v[162:165], off offset:256
	s_mov_b64 s[20:21], -1
	s_and_b64 vcc, exec, s[72:73]
	s_cbranch_vccnz .LBB0_904
	s_andn2_b64 vcc, exec, s[8:9]
	s_cbranch_vccnz .LBB0_903
	s_barrier
	s_branch .LBB0_903
